# dil_attn epilogue: hand-written, 16 old-tile loads issued together at loop exit, single wait (stacked on v2)
# speedup vs baseline: 1.0103x; 1.0048x over previous
; DI float fexp2(float x) { return __builtin_amdgcn_exp2f(x); }
; DI void dil_attn_phase(int wv, const bf16_t* qk, const bf16_t* vt, float* oacc, float* stats, bf16_t* ob, int g, int dil) {
;     ...
;         const float ltot = l + __shfl_xor(l, 32), inv = 1.f / ltot, lse2 = m + log2f(ltot);
;         float* st = stats + (qrow * 8 + head) * 2;
;         float a = 0.f, bw = 1.f, lrun = 1.f, mrun = lse2;
;         if (g > 0) { const float m0 = st_m0, lr0 = st_l0; const float mn = fmaxf(m0, lse2); a = fexp2(m0 - mn); bw = fexp2(lse2 - mn); lrun = lr0 * a + bw; mrun = mn; }
;         float* orow = oacc + qrow * 1024 + head * 128;
;         bf16_t* obrow = ob + qrow * 1024 + head * 128;
;         const float f = inv * bw, il = 1.f / lrun;
.LBB0_282:
	ds_bpermute_b32 v66, v238, v180
	v_readlane_b32 s2, v254, 26
	v_readlane_b32 s3, v254, 27
	v_readlane_b32 s12, v253, 38
	v_readlane_b32 s13, v253, 39
	s_lshl_b32 s26, s24, 2
	s_mov_b32 s27, 0
	v_lshlrev_b32_e32 v80, 2, v146
	v_mov_b32_e32 v81, 0
	s_nop 1
	v_lshl_add_u64 v[76:77], s[12:13], 0, v[154:155]
	v_lshl_add_u64 v[76:77], v[76:77], 0, s[26:27]
	v_lshl_add_u64 v[76:77], v[76:77], 0, v[80:81]
	s_and_b64 vcc, exec, s[2:3]
	s_cbranch_vccz .Ldil_noold
	global_load_dwordx4 v[82:85], v[76:77], off
	global_load_dwordx4 v[86:89], v[76:77], off offset:32
	global_load_dwordx4 v[90:93], v[76:77], off offset:64
	global_load_dwordx4 v[94:97], v[76:77], off offset:96
	global_load_dwordx4 v[98:101], v[76:77], off offset:128
	global_load_dwordx4 v[102:105], v[76:77], off offset:160
	global_load_dwordx4 v[106:109], v[76:77], off offset:192
	global_load_dwordx4 v[110:113], v[76:77], off offset:224
	global_load_dwordx4 v[114:117], v[76:77], off offset:256
	global_load_dwordx4 v[118:121], v[76:77], off offset:288
	global_load_dwordx4 v[122:125], v[76:77], off offset:320
	global_load_dwordx4 v[126:129], v[76:77], off offset:352
	global_load_dwordx4 v[130:133], v[76:77], off offset:384
	global_load_dwordx4 v[134:137], v[76:77], off offset:416
	global_load_dwordx4 v[138:141], v[76:77], off offset:448
	global_load_dwordx4 v[142:145], v[76:77], off offset:480
.Ldil_noold:
	s_waitcnt lgkmcnt(0)
	v_add_f32_e32 v69, v180, v66
	v_cmp_gt_f32_e32 vcc, s90, v69
	s_nop 1
	v_cndmask_b32_e64 v66, 0, 32, vcc
	v_ldexp_f32 v66, v69, v66
	v_log_f32_e32 v66, v66
	v_cndmask_b32_e32 v68, 0, v249, vcc
	s_and_b64 vcc, exec, s[2:3]
	v_sub_f32_e32 v66, v66, v68
	v_add_f32_e32 v66, v67, v66
	s_cbranch_vccz .LBB0_284
	v_max_f32_e32 v67, v66, v66
	s_waitcnt vmcnt(0)
	v_max_f32_e32 v68, v156, v156
	v_max_f32_e32 v70, v68, v67
	v_sub_f32_e32 v66, v66, v70
	v_exp_f32_e32 v72, v66
	v_sub_f32_e32 v66, v156, v70
	v_exp_f32_e32 v68, v66
	v_mov_b64_e32 v[66:67], v[70:71]
	v_fma_f32 v79, v157, v68, v72
	s_cbranch_execz .LBB0_285
	s_branch .LBB0_286

; DI float fexp2(float x) { return __builtin_amdgcn_exp2f(x); }
; DI void dil_attn_phase(int wv, const bf16_t* qk, const bf16_t* vt, float* oacc, float* stats, bf16_t* ob, int g, int dil) {
;     ...
;         if (g > 0) { const float m0 = st_m0, lr0 = st_l0; const float mn = fmaxf(m0, lse2); a = fexp2(m0 - mn); bw = fexp2(lse2 - mn); lrun = lr0 * a + bw; mrun = mn; }
;         float* orow = oacc + qrow * 1024 + head * 128;
;         bf16_t* obrow = ob + qrow * 1024 + head * 128;
;         const float f = inv * bw, il = 1.f / lrun;
; #pragma unroll
;         for (int d = 0; d < 4; ++d)
; #pragma unroll
;             for (int gq = 0; gq < 4; ++gq) { const int dv0 = d * 32 + 8 * gq + 4 * hh;
;                 f32x4 o = {O[d][4 * gq] * f, O[d][4 * gq + 1] * f, O[d][4 * gq + 2] * f, O[d][4 * gq + 3] * f};
;                 if (g > 0) { const f32x4 old = *(const f32x4*)(orow + dv0); o = o + old * a; }
.LBB0_286:
	v_div_scale_f32 v67, s[4:5], v69, v69, 1.0
	v_rcp_f32_e32 v70, v67
	v_div_scale_f32 v71, vcc, 1.0, v69, 1.0
	v_readlane_b32 s2, v253, 38
	v_fma_f32 v73, -v67, v70, 1.0
	v_fmac_f32_e32 v70, v73, v70
	v_mul_f32_e32 v73, v71, v70
	v_fma_f32 v74, -v67, v73, v71
	v_fmac_f32_e32 v73, v74, v70
	v_fma_f32 v67, -v67, v73, v71
	v_div_fmas_f32 v67, v67, v70, v73
	v_div_fixup_f32 v67, v67, v69, 1.0
	v_readlane_b32 s3, v253, 39
	s_lshl_b32 s56, s24, 2
	v_mul_f32_e32 v74, v67, v72
	v_lshl_add_u64 v[70:71], s[2:3], 0, v[154:155]
	v_lshl_add_u64 v[70:71], v[70:71], 0, s[56:57]
	v_mov_b32_e32 v69, v68
	v_div_scale_f32 v67, s[4:5], v79, v79, 1.0
	v_rcp_f32_e32 v73, v67
	v_readlane_b32 s2, v253, 36
	v_lshlrev_b64 v[70:71], 10, v[152:153]
	v_readlane_b32 s3, v253, 37
	v_fma_f32 v75, -v67, v73, 1.0
	v_fmac_f32_e32 v73, v75, v73
	v_div_scale_f32 v75, vcc, 1.0, v79, 1.0
	v_mul_f32_e32 v78, v75, v73
	v_fma_f32 v80, -v67, v78, v75
	v_fmac_f32_e32 v78, v80, v73
	v_fma_f32 v67, -v67, v78, v75
	v_lshl_add_u64 v[70:71], v[70:71], 1, s[2:3]
	s_lshl_b32 s56, s24, 1
	v_div_fmas_f32 v67, v67, v73, v78
	v_lshl_add_u64 v[70:71], v[70:71], 0, s[56:57]
	v_div_fixup_f32 v78, v67, v79, 1.0
	v_lshlrev_b32_e32 v80, 1, v146
	v_mov_b32_e32 v81, v1
	v_mov_b32_e32 v75, v74
	v_lshl_add_u64 v[70:71], v[70:71], 0, v[80:81]
	v_pk_mul_f32 v[50:51], v[50:51], v[74:75]
	v_pk_mul_f32 v[52:53], v[52:53], v[74:75]
	v_pk_mul_f32 v[54:55], v[54:55], v[74:75]
	v_pk_mul_f32 v[56:57], v[56:57], v[74:75]
	v_pk_mul_f32 v[58:59], v[58:59], v[74:75]
	v_pk_mul_f32 v[60:61], v[60:61], v[74:75]
	v_pk_mul_f32 v[62:63], v[62:63], v[74:75]
	v_pk_mul_f32 v[64:65], v[64:65], v[74:75]
	v_pk_mul_f32 v[34:35], v[34:35], v[74:75]
	v_pk_mul_f32 v[36:37], v[36:37], v[74:75]
	v_pk_mul_f32 v[38:39], v[38:39], v[74:75]
	v_pk_mul_f32 v[40:41], v[40:41], v[74:75]
	v_pk_mul_f32 v[42:43], v[42:43], v[74:75]
	v_pk_mul_f32 v[44:45], v[44:45], v[74:75]
	v_pk_mul_f32 v[46:47], v[46:47], v[74:75]
	v_pk_mul_f32 v[48:49], v[48:49], v[74:75]
	v_pk_mul_f32 v[18:19], v[18:19], v[74:75]
	v_pk_mul_f32 v[20:21], v[20:21], v[74:75]
	v_pk_mul_f32 v[22:23], v[22:23], v[74:75]
	v_pk_mul_f32 v[24:25], v[24:25], v[74:75]
	v_pk_mul_f32 v[26:27], v[26:27], v[74:75]
	v_pk_mul_f32 v[28:29], v[28:29], v[74:75]
	v_pk_mul_f32 v[30:31], v[30:31], v[74:75]
	v_pk_mul_f32 v[32:33], v[32:33], v[74:75]
	v_pk_mul_f32 v[2:3], v[2:3], v[74:75]
	v_pk_mul_f32 v[4:5], v[4:5], v[74:75]
	v_pk_mul_f32 v[6:7], v[6:7], v[74:75]
	v_pk_mul_f32 v[8:9], v[8:9], v[74:75]
	v_pk_mul_f32 v[10:11], v[10:11], v[74:75]
	v_pk_mul_f32 v[12:13], v[12:13], v[74:75]
	v_pk_mul_f32 v[14:15], v[14:15], v[74:75]
	v_pk_mul_f32 v[16:17], v[16:17], v[74:75]
	s_and_b64 vcc, exec, s[0:1]
	s_cbranch_vccnz .Ldil_st_f32
	s_waitcnt vmcnt(0)
	v_pk_fma_f32 v[50:51], v[68:69], v[82:83], v[50:51]
	v_pk_fma_f32 v[52:53], v[68:69], v[84:85], v[52:53]
	v_pk_fma_f32 v[54:55], v[68:69], v[86:87], v[54:55]
	v_pk_fma_f32 v[56:57], v[68:69], v[88:89], v[56:57]
	v_pk_fma_f32 v[58:59], v[68:69], v[90:91], v[58:59]
	v_pk_fma_f32 v[60:61], v[68:69], v[92:93], v[60:61]
	v_pk_fma_f32 v[62:63], v[68:69], v[94:95], v[62:63]
	v_pk_fma_f32 v[64:65], v[68:69], v[96:97], v[64:65]
	v_pk_fma_f32 v[34:35], v[68:69], v[98:99], v[34:35]
	v_pk_fma_f32 v[36:37], v[68:69], v[100:101], v[36:37]
	v_pk_fma_f32 v[38:39], v[68:69], v[102:103], v[38:39]
	v_pk_fma_f32 v[40:41], v[68:69], v[104:105], v[40:41]
	v_pk_fma_f32 v[42:43], v[68:69], v[106:107], v[42:43]
	v_pk_fma_f32 v[44:45], v[68:69], v[108:109], v[44:45]
	v_pk_fma_f32 v[46:47], v[68:69], v[110:111], v[46:47]
	v_pk_fma_f32 v[48:49], v[68:69], v[112:113], v[48:49]
	v_pk_fma_f32 v[18:19], v[68:69], v[114:115], v[18:19]
	v_pk_fma_f32 v[20:21], v[68:69], v[116:117], v[20:21]
	v_pk_fma_f32 v[22:23], v[68:69], v[118:119], v[22:23]
	v_pk_fma_f32 v[24:25], v[68:69], v[120:121], v[24:25]
	v_pk_fma_f32 v[26:27], v[68:69], v[122:123], v[26:27]
	v_pk_fma_f32 v[28:29], v[68:69], v[124:125], v[28:29]
	v_pk_fma_f32 v[30:31], v[68:69], v[126:127], v[30:31]
	v_pk_fma_f32 v[32:33], v[68:69], v[128:129], v[32:33]
	v_pk_fma_f32 v[2:3], v[68:69], v[130:131], v[2:3]
	v_pk_fma_f32 v[4:5], v[68:69], v[132:133], v[4:5]
	v_pk_fma_f32 v[6:7], v[68:69], v[134:135], v[6:7]
	v_pk_fma_f32 v[8:9], v[68:69], v[136:137], v[8:9]
	v_pk_fma_f32 v[10:11], v[68:69], v[138:139], v[10:11]
	v_pk_fma_f32 v[12:13], v[68:69], v[140:141], v[12:13]
	v_pk_fma_f32 v[14:15], v[68:69], v[142:143], v[14:15]
	v_pk_fma_f32 v[16:17], v[68:69], v[144:145], v[16:17]
	s_and_b64 vcc, exec, s[6:7]
	s_cbranch_vccz .Ldil_st_f32
; DI unsigned pk2(float lo, float hi) { f32x2 f = {lo, hi}; bf2_t v = __builtin_convertvector(f, bf2_t); return __builtin_bit_cast(unsigned, v); }
; DI void dil_attn_phase(int wv, const bf16_t* qk, const bf16_t* vt, float* oacc, float* stats, bf16_t* ob, int g, int dil) {
;     ...
;                 f32x4 o = {O[d][4 * gq] * f, O[d][4 * gq + 1] * f, O[d][4 * gq + 2] * f, O[d][4 * gq + 3] * f};
;                 if (g > 0) { const f32x4 old = *(const f32x4*)(orow + dv0); o = o + old * a; }
;                 if (g < 2) *(f32x4*)(orow + dv0) = o;
;                 else { u32x2 w; w.x = pk2(o.x * il, o.y * il); w.y = pk2(o.z * il, o.w * il); *(u32x2*)(obrow + dv0) = w; } }
;         if (g < 2 && hh == 0) { st[0] = mrun; st[1] = lrun; }
	v_pk_mul_f32 v[50:51], v[78:79], v[50:51] op_sel_hi:[0,1]
	v_pk_mul_f32 v[52:53], v[78:79], v[52:53] op_sel_hi:[0,1]
	v_pk_mul_f32 v[54:55], v[78:79], v[54:55] op_sel_hi:[0,1]
	v_pk_mul_f32 v[56:57], v[78:79], v[56:57] op_sel_hi:[0,1]
	v_pk_mul_f32 v[58:59], v[78:79], v[58:59] op_sel_hi:[0,1]
	v_pk_mul_f32 v[60:61], v[78:79], v[60:61] op_sel_hi:[0,1]
	v_pk_mul_f32 v[62:63], v[78:79], v[62:63] op_sel_hi:[0,1]
	v_pk_mul_f32 v[64:65], v[78:79], v[64:65] op_sel_hi:[0,1]
	v_pk_mul_f32 v[34:35], v[78:79], v[34:35] op_sel_hi:[0,1]
	v_pk_mul_f32 v[36:37], v[78:79], v[36:37] op_sel_hi:[0,1]
	v_pk_mul_f32 v[38:39], v[78:79], v[38:39] op_sel_hi:[0,1]
	v_pk_mul_f32 v[40:41], v[78:79], v[40:41] op_sel_hi:[0,1]
	v_pk_mul_f32 v[42:43], v[78:79], v[42:43] op_sel_hi:[0,1]
	v_pk_mul_f32 v[44:45], v[78:79], v[44:45] op_sel_hi:[0,1]
	v_pk_mul_f32 v[46:47], v[78:79], v[46:47] op_sel_hi:[0,1]
	v_pk_mul_f32 v[48:49], v[78:79], v[48:49] op_sel_hi:[0,1]
	v_pk_mul_f32 v[18:19], v[78:79], v[18:19] op_sel_hi:[0,1]
	v_pk_mul_f32 v[20:21], v[78:79], v[20:21] op_sel_hi:[0,1]
	v_pk_mul_f32 v[22:23], v[78:79], v[22:23] op_sel_hi:[0,1]
	v_pk_mul_f32 v[24:25], v[78:79], v[24:25] op_sel_hi:[0,1]
	v_pk_mul_f32 v[26:27], v[78:79], v[26:27] op_sel_hi:[0,1]
	v_pk_mul_f32 v[28:29], v[78:79], v[28:29] op_sel_hi:[0,1]
	v_pk_mul_f32 v[30:31], v[78:79], v[30:31] op_sel_hi:[0,1]
	v_pk_mul_f32 v[32:33], v[78:79], v[32:33] op_sel_hi:[0,1]
	v_pk_mul_f32 v[2:3], v[78:79], v[2:3] op_sel_hi:[0,1]
	v_pk_mul_f32 v[4:5], v[78:79], v[4:5] op_sel_hi:[0,1]
	v_pk_mul_f32 v[6:7], v[78:79], v[6:7] op_sel_hi:[0,1]
	v_pk_mul_f32 v[8:9], v[78:79], v[8:9] op_sel_hi:[0,1]
	v_pk_mul_f32 v[10:11], v[78:79], v[10:11] op_sel_hi:[0,1]
	v_pk_mul_f32 v[12:13], v[78:79], v[12:13] op_sel_hi:[0,1]
	v_pk_mul_f32 v[14:15], v[78:79], v[14:15] op_sel_hi:[0,1]
	v_pk_mul_f32 v[16:17], v[78:79], v[16:17] op_sel_hi:[0,1]
	v_cvt_pk_bf16_f32 v50, v50, v51
	v_cvt_pk_bf16_f32 v51, v52, v53
	global_store_dwordx2 v[70:71], v[50:51], off
	v_cvt_pk_bf16_f32 v54, v54, v55
	v_cvt_pk_bf16_f32 v55, v56, v57
	global_store_dwordx2 v[70:71], v[54:55], off offset:16
	v_cvt_pk_bf16_f32 v58, v58, v59
	v_cvt_pk_bf16_f32 v59, v60, v61
	global_store_dwordx2 v[70:71], v[58:59], off offset:32
	v_cvt_pk_bf16_f32 v62, v62, v63
	v_cvt_pk_bf16_f32 v63, v64, v65
	global_store_dwordx2 v[70:71], v[62:63], off offset:48
	v_cvt_pk_bf16_f32 v34, v34, v35
	v_cvt_pk_bf16_f32 v35, v36, v37
	global_store_dwordx2 v[70:71], v[34:35], off offset:64
	v_cvt_pk_bf16_f32 v38, v38, v39
	v_cvt_pk_bf16_f32 v39, v40, v41
	global_store_dwordx2 v[70:71], v[38:39], off offset:80
	v_cvt_pk_bf16_f32 v42, v42, v43
	v_cvt_pk_bf16_f32 v43, v44, v45
	global_store_dwordx2 v[70:71], v[42:43], off offset:96
	v_cvt_pk_bf16_f32 v46, v46, v47
	v_cvt_pk_bf16_f32 v47, v48, v49
	global_store_dwordx2 v[70:71], v[46:47], off offset:112
	v_cvt_pk_bf16_f32 v18, v18, v19
	v_cvt_pk_bf16_f32 v19, v20, v21
	global_store_dwordx2 v[70:71], v[18:19], off offset:128
	v_cvt_pk_bf16_f32 v22, v22, v23
	v_cvt_pk_bf16_f32 v23, v24, v25
	global_store_dwordx2 v[70:71], v[22:23], off offset:144
	v_cvt_pk_bf16_f32 v26, v26, v27
	v_cvt_pk_bf16_f32 v27, v28, v29
	global_store_dwordx2 v[70:71], v[26:27], off offset:160
	v_cvt_pk_bf16_f32 v30, v30, v31
	v_cvt_pk_bf16_f32 v31, v32, v33
	global_store_dwordx2 v[70:71], v[30:31], off offset:176
	v_cvt_pk_bf16_f32 v2, v2, v3
	v_cvt_pk_bf16_f32 v3, v4, v5
	global_store_dwordx2 v[70:71], v[2:3], off offset:192
	v_cvt_pk_bf16_f32 v6, v6, v7
	v_cvt_pk_bf16_f32 v7, v8, v9
	global_store_dwordx2 v[70:71], v[6:7], off offset:208
	v_cvt_pk_bf16_f32 v10, v10, v11
	v_cvt_pk_bf16_f32 v11, v12, v13
	global_store_dwordx2 v[70:71], v[10:11], off offset:224
	v_cvt_pk_bf16_f32 v14, v14, v15
	v_cvt_pk_bf16_f32 v15, v16, v17
	global_store_dwordx2 v[70:71], v[14:15], off offset:240
	s_branch .Ldil_ep_done
.Ldil_st_f32:
	global_store_dwordx4 v[76:77], v[50:53], off
	global_store_dwordx4 v[76:77], v[54:57], off offset:32
	global_store_dwordx4 v[76:77], v[58:61], off offset:64
	global_store_dwordx4 v[76:77], v[62:65], off offset:96
	global_store_dwordx4 v[76:77], v[34:37], off offset:128
	global_store_dwordx4 v[76:77], v[38:41], off offset:160
	global_store_dwordx4 v[76:77], v[42:45], off offset:192
	global_store_dwordx4 v[76:77], v[46:49], off offset:224
	global_store_dwordx4 v[76:77], v[18:21], off offset:256
	global_store_dwordx4 v[76:77], v[22:25], off offset:288
	global_store_dwordx4 v[76:77], v[26:29], off offset:320
	global_store_dwordx4 v[76:77], v[30:33], off offset:352
	global_store_dwordx4 v[76:77], v[2:5], off offset:384
	global_store_dwordx4 v[76:77], v[6:9], off offset:416
	global_store_dwordx4 v[76:77], v[10:13], off offset:448
	global_store_dwordx4 v[76:77], v[14:17], off offset:480
.Ldil_ep_done:
	s_and_saveexec_b64 s[0:1], s[8:9]
	s_cbranch_execz .LBB0_276
.LBB0_383:
	s_lshl_b32 s56, s23, 3
	v_mov_b32_e32 v67, v79
	v_lshl_add_u64 v[2:3], v[150:151], 0, s[56:57]
	global_store_dwordx2 v[2:3], v[66:67], off
	s_branch .LBB0_276
